# k29 + HGRN phase C LDS-address multiplies by 272 strength-reduced to shift-adds (8 sites, exact)
# baseline (speedup 1.0000x reference)
; #define LAS __attribute__((address_space(3)))
; __device__ __forceinline__ unsigned pk2(float lo, float hi) { const f32x2 v = {lo, hi}; const bf16x2_t b = __builtin_convertvector(v, bf16x2_t); return __builtin_bit_cast(unsigned, b); }
; __device__ __forceinline__ void write_st(const Frame& F, const f32x16 (&S)[2]) {
;     LAS unsigned char* L = F.lds;
;     const int w = F.wave, lane = F.lane, r = lane & 31, hh = lane >> 5, db = w >> 1;
;     const LAS float* em = (const LAS float*)(L + O_EM) + 32 * db + 4 * hh;
;     f32x4 sc[4];
; #pragma unroll
;     for (int g = 0; g < 4; ++g) sc[g] = *(const LAS f32x4*)(em + 8 * g);
; #pragma unroll
;     for (int blk = 0; blk < 2; ++blk) {
;         const int eb = 2 * (w & 1) + blk;
;         LAS unsigned char* sp = L + O_ST + (32 * eb + r) * S128 + (32 * db + 4 * hh) * 2;
; #pragma unroll
;         for (int g = 0; g < 4; ++g) {
;             u32x2 o; o.x = pk2(S[blk][4 * g] * sc[g].x, S[blk][4 * g + 1] * sc[g].y); o.y = pk2(S[blk][4 * g + 2] * sc[g].z, S[blk][4 * g + 3] * sc[g].w);
;             *(LAS u32x2*)(sp + 16 * g) = o;
;         }
;     }
; template <int DIR>
; __device__ __forceinline__ void hgrn_c_dir(const Frame& F, int l, int it_lat  , int h, int row0, bf16_t* QV, unsigned* ofs  , bool dry,
;                                            unsigned (&rf)[8], unsigned (&rq)[8], unsigned (&rv)[8], bool pre, int itn  ) {
;     ...
;         hg::load8(rq, rsQ, lofx, (unsigned)rown * 4096u, 4096u);
;         __syncthreads();
;         hg::write_st(F, S);
;         if (w < 4) {
;             const int sb = w >> 1, tbk = w & 1;
;             const bool dead = DIR == 0 ? (sb == 1 && tbk == 0) : (sb == 0 && tbk == 1);
;             f32x16 P;
; #pragma unroll
;             for (int i = 0; i < 16; ++i) P[i] = 0.f;
;             if (!dead) {
;                 const LAS unsigned char* ap = L + hg::O_KH + (32 * sb + r) * hg::S128 + 16 * hh;
;                 const LAS unsigned char* bp = L + hg::O_QH + (32 * tbk + r) * hg::S128 + 16 * hh;
; #pragma unroll
;                 for (int kq = 0; kq < 8; ++kq) {
;                     const bf16x8 a = *(const LAS bf16x8*)(ap + 32 * kq);
;                     const bf16x8 bb = *(const LAS bf16x8*)(bp + 32 * kq);
;                     P = __builtin_amdgcn_mfma_f32_32x32x16_bf16(a, bb, P, 0, 0, 0);
;                 }
;             }
.LBB0_734:
	buffer_load_dword v144, v0, s[12:15], s4 offen
	buffer_load_dword v143, v0, s[12:15], s28 offen
	buffer_load_dword v119, v0, s[12:15], s30 offen
	buffer_load_dword v118, v0, s[12:15], s31 offen
	buffer_load_dword v117, v0, s[12:15], s7 offen
	buffer_load_dword v116, v0, s[12:15], s16 offen
	buffer_load_dword v115, v0, s[12:15], s9 offen
	buffer_load_dword v114, v0, s[12:15], s17 offen
	s_waitcnt lgkmcnt(0)
	s_barrier
	ds_read_b128 v[2:5], v138
	ds_read_b128 v[6:9], v138 offset:32
	ds_read_b128 v[10:13], v138 offset:64
	ds_read_b128 v[48:51], v138 offset:96
	v_add_u32_e32 v173, 0x2000, v142
	s_waitcnt lgkmcnt(3)
	v_pk_mul_f32 v[52:53], v[16:17], v[2:3]
	v_pk_mul_f32 v[54:55], v[18:19], v[4:5]
	v_pk_mul_f32 v[2:3], v[32:33], v[2:3]
	v_pk_mul_f32 v[4:5], v[34:35], v[4:5]
	v_cvt_pk_bf16_f32 v52, v52, v53
	v_cvt_pk_bf16_f32 v53, v54, v55
	s_waitcnt lgkmcnt(2)
	v_pk_mul_f32 v[54:55], v[20:21], v[6:7]
	v_cvt_pk_bf16_f32 v2, v2, v3
	v_cvt_pk_bf16_f32 v3, v4, v5
	v_pk_mul_f32 v[4:5], v[36:37], v[6:7]
	v_pk_mul_f32 v[6:7], v[38:39], v[8:9]
	v_pk_mul_f32 v[56:57], v[22:23], v[8:9]
	v_cvt_pk_bf16_f32 v4, v4, v5
	v_cvt_pk_bf16_f32 v5, v6, v7
	v_cvt_pk_bf16_f32 v54, v54, v55
	v_cvt_pk_bf16_f32 v55, v56, v57
	ds_write2_b64 v173, v[2:3], v[4:5] offset0:64 offset1:66
	s_waitcnt lgkmcnt(2)
	v_pk_mul_f32 v[2:3], v[40:41], v[10:11]
	v_pk_mul_f32 v[4:5], v[42:43], v[12:13]
	ds_write2_b64 v142, v[52:53], v[54:55] offset1:2
	v_pk_mul_f32 v[52:53], v[24:25], v[10:11]
	v_pk_mul_f32 v[54:55], v[26:27], v[12:13]
	v_cvt_pk_bf16_f32 v2, v2, v3
	v_cvt_pk_bf16_f32 v3, v4, v5
	s_waitcnt lgkmcnt(2)
	v_pk_mul_f32 v[4:5], v[44:45], v[48:49]
	v_pk_mul_f32 v[6:7], v[46:47], v[50:51]
	v_cvt_pk_bf16_f32 v52, v52, v53
	v_cvt_pk_bf16_f32 v53, v54, v55
	v_pk_mul_f32 v[54:55], v[28:29], v[48:49]
	v_pk_mul_f32 v[56:57], v[30:31], v[50:51]
	v_cvt_pk_bf16_f32 v4, v4, v5
	v_cvt_pk_bf16_f32 v5, v6, v7
	v_cndmask_b32_e64 v6, 0, 1, s[52:53]
	v_cvt_pk_bf16_f32 v54, v54, v55
	v_cvt_pk_bf16_f32 v55, v56, v57
	v_cmp_ne_u32_e64 s[72:73], 1, v6
	s_andn2_b64 vcc, exec, s[52:53]
	ds_write2_b64 v142, v[52:53], v[54:55] offset0:4 offset1:6
	ds_write2_b64 v173, v[2:3], v[4:5] offset0:68 offset1:70
	s_cbranch_vccnz .LBB0_739
	v_readlane_b32 s16, v251, 60
	v_readlane_b32 s17, v251, 61
	s_andn2_b64 vcc, exec, s[16:17]
	s_cbranch_vccnz .LBB0_737
	v_readlane_b32 s4, v251, 62
	v_lshlrev_b32_e32 v3, 4, v175
	s_nop 0
	v_add_u32_e32 v2, s4, v174
	v_lshl_add_u32 v2, v2, 4, v2
	v_lshlrev_b32_e32 v2, 4, v2
	v_add3_u32 v12, 0, v2, v3
	ds_read_b128 v[4:7], v12 offset:17408
	v_readlane_b32 s4, v251, 63
	s_nop 1
	v_add_u32_e32 v2, s4, v174
	v_lshl_add_u32 v8, v2, 4, v2
	v_lshlrev_b32_e32 v8, 4, v8
	v_add3_u32 v3, 0, v8, v3
	ds_read_b128 v[8:11], v3
	s_waitcnt lgkmcnt(0)
	v_mfma_f32_32x32x16_bf16 v[48:63], v[4:7], v[8:11], 0
	ds_read_b128 v[4:7], v12 offset:17440
	ds_read_b128 v[8:11], v3 offset:32
	s_waitcnt lgkmcnt(0)
	v_mfma_f32_32x32x16_bf16 v[48:63], v[4:7], v[8:11], v[48:63]
	ds_read_b128 v[4:7], v12 offset:17472
	ds_read_b128 v[8:11], v3 offset:64
	s_waitcnt lgkmcnt(0)
	v_mfma_f32_32x32x16_bf16 v[48:63], v[4:7], v[8:11], v[48:63]
	ds_read_b128 v[4:7], v12 offset:17504
	ds_read_b128 v[8:11], v3 offset:96
	s_waitcnt lgkmcnt(0)
	v_mfma_f32_32x32x16_bf16 v[48:63], v[4:7], v[8:11], v[48:63]
	ds_read_b128 v[4:7], v12 offset:17536
	ds_read_b128 v[8:11], v3 offset:128
	s_waitcnt lgkmcnt(0)
	v_mfma_f32_32x32x16_bf16 v[48:63], v[4:7], v[8:11], v[48:63]
	ds_read_b128 v[4:7], v12 offset:17568
	ds_read_b128 v[8:11], v3 offset:160
	s_waitcnt lgkmcnt(0)
	v_mfma_f32_32x32x16_bf16 v[48:63], v[4:7], v[8:11], v[48:63]
	ds_read_b128 v[4:7], v12 offset:17600
	ds_read_b128 v[8:11], v3 offset:192
	s_waitcnt lgkmcnt(0)
	v_mfma_f32_32x32x16_bf16 v[48:63], v[4:7], v[8:11], v[48:63]
	ds_read_b128 v[4:7], v12 offset:17632
	ds_read_b128 v[8:11], v3 offset:224
	s_waitcnt lgkmcnt(0)
	v_mfma_f32_32x32x16_bf16 v[48:63], v[4:7], v[8:11], v[48:63]
	s_branch .LBB0_738

; #define LAS __attribute__((address_space(3)))
; template <int DIR>
; __device__ __forceinline__ void hgrn_c_dir(const Frame& F, int l, int it_lat  , int h, int row0, bf16_t* QV, unsigned* ofs  , bool dry,
;                                            unsigned (&rf)[8], unsigned (&rq)[8], unsigned (&rv)[8], bool pre, int itn  ) {
;     ...
;         __syncthreads();
;         f32x16 o;
; #pragma unroll
;         for (int i = 0; i < 16; ++i) o[i] = 0.f;
;         {   const LAS unsigned char* ap = L + hg::O_ST + (32 * ebo + r) * hg::S128 + 16 * hh;
;             const LAS unsigned char* bp = L + hg::O_QH + (32 * tb + r) * hg::S128 + 16 * hh;
.LBB0_739:
	v_add_u32_e32 v3, s33, v174
	v_lshlrev_b32_e32 v2, 4, v175
	v_lshl_add_u32 v4, v3, 4, v3
	v_lshlrev_b32_e32 v4, 4, v4
	v_lshl_add_u32 v5, v174, 4, v174
	v_lshlrev_b32_e32 v5, 4, v5
	v_readlane_b32 s4, v254, 50
	v_mov_b32_e32 v48, 0
	v_add3_u32 v4, 0, v4, v2
	v_add3_u32 v5, v5, v2, s4
	s_mov_b32 s4, 0
	v_mov_b32_e32 v49, v48
	v_mov_b32_e32 v50, v48
	v_mov_b32_e32 v51, v48
	v_mov_b32_e32 v52, v48
	v_mov_b32_e32 v53, v48
	v_mov_b32_e32 v54, v48
	v_mov_b32_e32 v55, v48
	v_mov_b32_e32 v56, v48
	v_mov_b32_e32 v57, v48
	v_mov_b32_e32 v58, v48
	v_mov_b32_e32 v59, v48
	v_mov_b32_e32 v60, v48
	v_mov_b32_e32 v61, v48
	v_mov_b32_e32 v62, v48
	v_mov_b32_e32 v63, v48
	s_waitcnt lgkmcnt(0)
	s_barrier

; #define LAS __attribute__((address_space(3)))
; __device__ __forceinline__ unsigned pk2(float lo, float hi) { const f32x2 v = {lo, hi}; const bf16x2_t b = __builtin_convertvector(v, bf16x2_t); return __builtin_bit_cast(unsigned, b); }
; __device__ __forceinline__ void write_st(const Frame& F, const f32x16 (&S)[2]) {
;     LAS unsigned char* L = F.lds;
;     const int w = F.wave, lane = F.lane, r = lane & 31, hh = lane >> 5, db = w >> 1;
;     const LAS float* em = (const LAS float*)(L + O_EM) + 32 * db + 4 * hh;
;     f32x4 sc[4];
; #pragma unroll
;     for (int g = 0; g < 4; ++g) sc[g] = *(const LAS f32x4*)(em + 8 * g);
; #pragma unroll
;     for (int blk = 0; blk < 2; ++blk) {
;         const int eb = 2 * (w & 1) + blk;
;         LAS unsigned char* sp = L + O_ST + (32 * eb + r) * S128 + (32 * db + 4 * hh) * 2;
; #pragma unroll
;         for (int g = 0; g < 4; ++g) {
;             u32x2 o; o.x = pk2(S[blk][4 * g] * sc[g].x, S[blk][4 * g + 1] * sc[g].y); o.y = pk2(S[blk][4 * g + 2] * sc[g].z, S[blk][4 * g + 3] * sc[g].w);
;             *(LAS u32x2*)(sp + 16 * g) = o;
;         }
;     }
; template <int DIR>
; __device__ __forceinline__ void hgrn_c_dir(const Frame& F, int l, int it_lat  , int h, int row0, bf16_t* QV, unsigned* ofs  , bool dry,
;                                            unsigned (&rf)[8], unsigned (&rq)[8], unsigned (&rv)[8], bool pre, int itn  ) {
;     ...
;         hg::load8(rq, rsQ, lofx, (unsigned)rown * 4096u, 4096u);
;         __syncthreads();
;         hg::write_st(F, S);
;         if (w < 4) {
;             const int sb = w >> 1, tbk = w & 1;
;             const bool dead = DIR == 0 ? (sb == 1 && tbk == 0) : (sb == 0 && tbk == 1);
;             f32x16 P;
; #pragma unroll
;             for (int i = 0; i < 16; ++i) P[i] = 0.f;
;             if (!dead) {
;                 const LAS unsigned char* ap = L + hg::O_KH + (32 * sb + r) * hg::S128 + 16 * hh;
;                 const LAS unsigned char* bp = L + hg::O_QH + (32 * tbk + r) * hg::S128 + 16 * hh;
; #pragma unroll
;                 for (int kq = 0; kq < 8; ++kq) {
;                     const bf16x8 a = *(const LAS bf16x8*)(ap + 32 * kq);
;                     const bf16x8 bb = *(const LAS bf16x8*)(bp + 32 * kq);
;                     P = __builtin_amdgcn_mfma_f32_32x32x16_bf16(a, bb, P, 0, 0, 0);
;                 }
;             }
.LBB0_790:
	buffer_load_dword v144, v178, s[12:15], s16 offen
	buffer_load_dword v143, v178, s[12:15], s66 offen
	buffer_load_dword v119, v178, s[12:15], s67 offen
	buffer_load_dword v118, v178, s[12:15], s62 offen
	buffer_load_dword v117, v178, s[12:15], s7 offen
	buffer_load_dword v116, v178, s[12:15], s17 offen
	buffer_load_dword v115, v178, s[12:15], s31 offen
	buffer_load_dword v114, v178, s[12:15], s9 offen
	s_waitcnt lgkmcnt(0)
	s_barrier
	ds_read_b128 v[2:5], v138
	ds_read_b128 v[6:9], v138 offset:32
	ds_read_b128 v[10:13], v138 offset:64
	ds_read_b128 v[48:51], v138 offset:96
	s_and_b64 vcc, exec, s[72:73]
	s_waitcnt lgkmcnt(3)
	v_pk_mul_f32 v[52:53], v[16:17], v[2:3]
	v_pk_mul_f32 v[54:55], v[18:19], v[4:5]
	v_pk_mul_f32 v[2:3], v[32:33], v[2:3]
	v_pk_mul_f32 v[4:5], v[34:35], v[4:5]
	v_cvt_pk_bf16_f32 v52, v52, v53
	v_cvt_pk_bf16_f32 v53, v54, v55
	s_waitcnt lgkmcnt(2)
	v_pk_mul_f32 v[54:55], v[20:21], v[6:7]
	v_pk_mul_f32 v[56:57], v[22:23], v[8:9]
	v_cvt_pk_bf16_f32 v2, v2, v3
	v_cvt_pk_bf16_f32 v3, v4, v5
	v_pk_mul_f32 v[4:5], v[36:37], v[6:7]
	v_pk_mul_f32 v[6:7], v[38:39], v[8:9]
	v_cvt_pk_bf16_f32 v54, v54, v55
	v_cvt_pk_bf16_f32 v55, v56, v57
	v_cvt_pk_bf16_f32 v4, v4, v5
	v_cvt_pk_bf16_f32 v5, v6, v7
	ds_write2_b64 v142, v[52:53], v[54:55] offset1:2
	s_waitcnt lgkmcnt(2)
	v_pk_mul_f32 v[52:53], v[24:25], v[10:11]
	v_pk_mul_f32 v[54:55], v[26:27], v[12:13]
	ds_write2_b64 v173, v[2:3], v[4:5] offset0:64 offset1:66
	v_pk_mul_f32 v[2:3], v[40:41], v[10:11]
	v_pk_mul_f32 v[4:5], v[42:43], v[12:13]
	v_cvt_pk_bf16_f32 v52, v52, v53
	v_cvt_pk_bf16_f32 v53, v54, v55
	s_waitcnt lgkmcnt(2)
	v_pk_mul_f32 v[54:55], v[28:29], v[48:49]
	v_pk_mul_f32 v[56:57], v[30:31], v[50:51]
	v_cvt_pk_bf16_f32 v2, v2, v3
	v_cvt_pk_bf16_f32 v3, v4, v5
	v_pk_mul_f32 v[4:5], v[44:45], v[48:49]
	v_pk_mul_f32 v[6:7], v[46:47], v[50:51]
	v_cvt_pk_bf16_f32 v54, v54, v55
	v_cvt_pk_bf16_f32 v55, v56, v57
	v_cvt_pk_bf16_f32 v4, v4, v5
	v_cvt_pk_bf16_f32 v5, v6, v7
	ds_write2_b64 v142, v[52:53], v[54:55] offset0:4 offset1:6
	ds_write2_b64 v173, v[2:3], v[4:5] offset0:68 offset1:70
	s_cbranch_vccnz .LBB0_796
	v_readlane_b32 s38, v252, 7
	v_readlane_b32 s39, v252, 8
	v_readlane_b32 s7, v251, 63
	s_mov_b64 s[16:17], -1
	s_and_b64 vcc, exec, s[38:39]
	v_add_u32_e32 v3, s7, v0
	s_cbranch_vccz .LBB0_793
	v_readlane_b32 s7, v251, 62
	v_lshlrev_b32_e32 v8, 4, v177
	s_mov_b64 s[16:17], 0
	v_add_u32_e32 v2, s7, v0
	v_lshl_add_u32 v2, v2, 4, v2
	v_lshlrev_b32_e32 v2, 4, v2
	v_add3_u32 v12, 0, v2, v8
	ds_read_b128 v[4:7], v12 offset:17408
	v_readlane_b32 s7, v251, 63
	s_nop 1
	v_add_u32_e32 v2, s7, v0
	v_lshl_add_u32 v9, v2, 4, v2
	v_lshlrev_b32_e32 v9, 4, v9
	v_add3_u32 v13, 0, v9, v8
	ds_read_b128 v[8:11], v13
	s_waitcnt lgkmcnt(0)
	v_mfma_f32_32x32x16_bf16 v[48:63], v[4:7], v[8:11], 0
	ds_read_b128 v[4:7], v12 offset:17440
	ds_read_b128 v[8:11], v13 offset:32
	s_waitcnt lgkmcnt(0)
	v_mfma_f32_32x32x16_bf16 v[48:63], v[4:7], v[8:11], v[48:63]
	ds_read_b128 v[4:7], v12 offset:17472
	ds_read_b128 v[8:11], v13 offset:64
	s_waitcnt lgkmcnt(0)
	v_mfma_f32_32x32x16_bf16 v[48:63], v[4:7], v[8:11], v[48:63]
	ds_read_b128 v[4:7], v12 offset:17504
	ds_read_b128 v[8:11], v13 offset:96
	s_waitcnt lgkmcnt(0)
	v_mfma_f32_32x32x16_bf16 v[48:63], v[4:7], v[8:11], v[48:63]
	ds_read_b128 v[4:7], v12 offset:17536
	ds_read_b128 v[8:11], v13 offset:128
	s_waitcnt lgkmcnt(0)
	v_mfma_f32_32x32x16_bf16 v[48:63], v[4:7], v[8:11], v[48:63]
	ds_read_b128 v[4:7], v12 offset:17568
	ds_read_b128 v[8:11], v13 offset:160
	s_waitcnt lgkmcnt(0)
	v_mfma_f32_32x32x16_bf16 v[48:63], v[4:7], v[8:11], v[48:63]
	ds_read_b128 v[4:7], v12 offset:17600
	ds_read_b128 v[8:11], v13 offset:192
	s_waitcnt lgkmcnt(0)
	v_mfma_f32_32x32x16_bf16 v[48:63], v[4:7], v[8:11], v[48:63]
	ds_read_b128 v[4:7], v12 offset:17632
	ds_read_b128 v[8:11], v13 offset:224
	s_waitcnt lgkmcnt(0)
	v_mfma_f32_32x32x16_bf16 v[48:63], v[4:7], v[8:11], v[48:63]

; #define LAS __attribute__((address_space(3)))
; template <int DIR>
; __device__ __forceinline__ void hgrn_c_dir(const Frame& F, int l, int it_lat  , int h, int row0, bf16_t* QV, unsigned* ofs  , bool dry,
;                                            unsigned (&rf)[8], unsigned (&rq)[8], unsigned (&rv)[8], bool pre, int itn  ) {
;     ...
;         __syncthreads();
;         f32x16 o;
; #pragma unroll
;         for (int i = 0; i < 16; ++i) o[i] = 0.f;
;         {   const LAS unsigned char* ap = L + hg::O_ST + (32 * ebo + r) * hg::S128 + 16 * hh;
;             const LAS unsigned char* bp = L + hg::O_QH + (32 * tb + r) * hg::S128 + 16 * hh;
.LBB0_796:
	v_add_u32_e32 v90, s33, v0
	v_lshlrev_b32_e32 v2, 4, v177
	v_lshl_add_u32 v3, v90, 4, v90
	v_lshlrev_b32_e32 v3, 4, v3
	v_lshl_add_u32 v4, v0, 4, v0
	v_lshlrev_b32_e32 v4, 4, v4
	v_readlane_b32 s7, v254, 50
	v_mov_b32_e32 v48, 0
	v_add3_u32 v3, 0, v3, v2
	v_add3_u32 v4, v4, v2, s7
	s_mov_b32 s7, 0
	v_mov_b32_e32 v49, v48
	v_mov_b32_e32 v50, v48
	v_mov_b32_e32 v51, v48
	v_mov_b32_e32 v52, v48
	v_mov_b32_e32 v53, v48
	v_mov_b32_e32 v54, v48
	v_mov_b32_e32 v55, v48
	v_mov_b32_e32 v56, v48
	v_mov_b32_e32 v57, v48
	v_mov_b32_e32 v58, v48
	v_mov_b32_e32 v59, v48
	v_mov_b32_e32 v60, v48
	v_mov_b32_e32 v61, v48
	v_mov_b32_e32 v62, v48
	v_mov_b32_e32 v63, v48
	s_waitcnt lgkmcnt(0)
	s_barrier
